# attention: per-unit precomputed fragment LDS addresses, LDS stage folded into ds_read immediates (two code variants per stage)
# speedup vs baseline: 1.0145x; 1.0058x over previous
; #define LAS __attribute__((address_space(3)))
; DI void gload_lds16(const void* g, LAS char* l) { __builtin_amdgcn_global_load_lds((const unsigned*)g, (LAS unsigned*)l, 16, 0, 0); }
; DI void phase_attn(const Params& p, int l, LAS char* lds) {
;     ...
;         const int unit = k * G + ((k & 1) ? (G - 1 - (int)blockIdx.x) : (int)blockIdx.x);
;         if (unit >= NUNITS) continue;
;         const int qt = 32 - unit / 64, bh = unit & 63, b = bh >> 3, hd = bh & 7;
;         const int q0w = qt * 128 + w * 32;
;         const int nkt = (2 * qt + 2 < 65) ? 2 * qt + 2 : 65;
;         bf16x8 qf[6];
;         {
;             const int tq = (q0w + qi < LSEQ) ? q0w + qi : LSEQ - 1;
;             const bf16_t* qp = Q + ((size_t)(b * LSEQ + tq)) * 768 + hd * 96 + 8 * hh;
; #pragma unroll
;             for (int s = 0; s < 6; ++s) qf[s] = *(const bf16x8*)(qp + 16 * s);
;         }
;         const bf16_t* Knb = Kn + (size_t)b * LSEQ * 512 + hd * 64;
;         const bf16_t* Krb = Kr + (size_t)b * LSEQ * 32;
;         const bf16_t* Vtb = Vt + (size_t)bh * 64 * LP;
;         auto issue = [&](int stage, int kt) {
;             LAS char* base = lds + stage * 20480 + w * 1024;
; #pragma unroll
;             for (int j = 0; j < 3; ++j) {
;                 int tk = kt * 64 + krow_[j]; tk = (tk < LSEQ) ? tk : LSEQ - 1;
;                 const bf16_t* src = (kc_[j] < 8) ? Knb + (size_t)tk * 512 + kc_[j] * 8 : Krb + (size_t)tk * 32 + (kc_[j] - 8) * 8;
;                 gload_lds16(src, base + j * 4096);
;             }
; #pragma unroll
;             for (int j = 0; j < 2; ++j) gload_lds16(Vtb + (size_t)vrow_[j] * LP + kt * 64 + vc_[j] * 8, base + 12288 + j * 4096);
;         };
;         f32x16 o0, o1;
; #pragma unroll
;         for (int r = 0; r < 16; ++r) { o0[r] = 0.f; o1[r] = 0.f; }
;         float m_run = -INFINITY, l_run = 0.f;
;         issue(0, 0);
;     ...
;             for (int s = 0; s < 6; ++s) {
;                 const int pos = ((2 * s + hh) ^ ksw) << 4;
;                 const bf16x8 k0 = *(LAS bf16x8*)(st + qi * 192 + pos);
;                 const bf16x8 k1 = *(LAS bf16x8*)(st + (qi + 32) * 192 + pos);
.LBB0_282:
	s_bitcmp0_b32 s54, 0
	s_cselect_b32 s1, s2, s75
	s_add_i32 s0, s1, s0
	s_cmpk_gt_i32 s0, 0x83f
	s_cbranch_scc1 .LBB0_281
	s_ashr_i32 s1, s0, 31
	s_lshr_b32 s1, s1, 26
	s_add_i32 s1, s0, s1
	s_ashr_i32 s1, s1, 6
	s_sub_i32 s4, 0, s1
	s_sub_i32 s1, 32, s1
	v_lshl_add_u32 v123, s1, 7, v141
	v_or_b32_e32 v122, v123, v91
	s_bfe_u32 s5, s0, 0x30003
	v_cmp_gt_i32_e64 s[44:45], s25, v122
	s_and_b32 s8, s0, 63
	s_and_b32 s6, s0, 7
	s_lshl_b32 s0, s1, 1
	v_cndmask_b32_e64 v1, v169, v122, s[44:45]
	s_mul_i32 s50, s5, 0x1010
	s_add_i32 s7, s0, 2
	v_add_u32_e32 v1, s50, v1
	v_mov_b64_e32 v[2:3], s[12:13]
	s_movk_i32 s0, 0x600
	v_mad_i64_i32 v[2:3], s[0:1], v1, s0, v[2:3]
	s_lshl_b32 s5, s50, 10
	s_lshl_b32 s0, s6, 6
	s_lshl_b32 s9, s50, 6
	s_cmp_gt_u32 s4, 0xffffffdf
	s_cselect_b32 s1, s7, 0x41
	s_add_u32 s4, s11, s5
	s_mul_i32 s34, s6, 0xc0
	s_addc_u32 s5, s74, 0
	s_lshl_b32 s6, s6, 7
	s_add_u32 s4, s4, s6
	s_addc_u32 s5, s5, 0
	s_add_u32 s6, s72, s9
	v_lshl_add_u64 v[2:3], v[2:3], 0, s[34:35]
	s_addc_u32 s7, s73, 0
	v_lshl_add_u64 v[2:3], v[2:3], 0, v[148:149]
	v_lshl_add_u64 v[4:5], s[6:7], 0, v[92:93]
	global_load_dwordx4 v[66:69], v[2:3], off
	global_load_dwordx4 v[70:73], v[2:3], off offset:32
	global_load_dwordx4 v[74:77], v[2:3], off offset:64
	global_load_dwordx4 v[78:81], v[2:3], off offset:96
	global_load_dwordx4 v[82:85], v[2:3], off offset:128
	global_load_dwordx4 v[86:89], v[2:3], off offset:160
	v_lshl_add_u64 v[2:3], s[4:5], 0, v[94:95]
	v_lshl_add_u64 v[4:5], v[4:5], 0, v[110:111]
	v_lshl_add_u64 v[2:3], v[2:3], 0, v[108:109]
	v_lshl_add_u64 v[4:5], v[4:5], 0, s[36:37]
	v_readfirstlane_b32 s10, v140
	v_cndmask_b32_e64 v3, v5, v3, s[38:39]
	v_cndmask_b32_e64 v2, v4, v2, s[38:39]
	s_mov_b32 m0, s10
	v_lshl_add_u64 v[4:5], s[6:7], 0, v[96:97]
	global_load_lds_dwordx4 v[2:3], off
	v_lshl_add_u64 v[2:3], s[4:5], 0, v[98:99]
	v_lshl_add_u64 v[4:5], v[4:5], 0, v[114:115]
	v_add_u32_e32 v1, 0x1000, v140
	v_lshl_add_u64 v[2:3], v[2:3], 0, v[112:113]
	v_lshl_add_u64 v[4:5], v[4:5], 0, s[36:37]
	v_readfirstlane_b32 s10, v1
	v_cndmask_b32_e64 v3, v5, v3, s[40:41]
	v_cndmask_b32_e64 v2, v4, v2, s[40:41]
	s_mov_b32 m0, s10
	v_lshl_add_u64 v[4:5], s[6:7], 0, v[100:101]
	s_mul_i32 s8, s8, 0x84000
	global_load_lds_dwordx4 v[2:3], off
	v_lshl_add_u64 v[2:3], s[4:5], 0, v[102:103]
	v_lshl_add_u64 v[4:5], v[4:5], 0, v[118:119]
	v_add_u32_e32 v1, 0x2000, v140
	s_add_u32 s8, s76, s8
	v_lshl_add_u64 v[2:3], v[2:3], 0, v[116:117]
	v_lshl_add_u64 v[4:5], v[4:5], 0, s[36:37]
	v_readfirstlane_b32 s10, v1
	s_addc_u32 s9, s77, 0
	v_cndmask_b32_e64 v3, v5, v3, s[42:43]
	v_cndmask_b32_e64 v2, v4, v2, s[42:43]
	s_mov_b32 m0, s10
	v_add_u32_e32 v1, 0x3000, v140
	global_load_lds_dwordx4 v[2:3], off
	v_lshl_add_u64 v[2:3], s[8:9], 0, v[104:105]
	v_mov_b32_e32 v121, v149
	v_readfirstlane_b32 s10, v1
	v_add_u32_e32 v1, 0x4000, v140
	v_lshl_add_u64 v[124:125], v[2:3], 0, v[120:121]
	s_mov_b32 m0, s10
	v_lshl_add_u64 v[2:3], s[8:9], 0, v[106:107]
	v_readfirstlane_b32 s8, v1
	global_load_lds_dwordx4 v[124:125], off
	v_lshl_add_u64 v[126:127], v[2:3], 0, v[120:121]
	s_mov_b32 m0, s8
	v_mov_b32_e32 v14, v0
	global_load_lds_dwordx4 v[126:127], off
	v_mov_b32_e32 v15, v0
	v_mov_b32_e32 v1, v0
	v_mov_b32_e32 v2, v0
	v_mov_b32_e32 v3, v0
	v_mov_b32_e32 v4, v0
	v_mov_b32_e32 v5, v0
	v_mov_b32_e32 v6, v0
	v_mov_b32_e32 v7, v0
	v_mov_b32_e32 v8, v0
	v_mov_b32_e32 v9, v0
	v_mov_b32_e32 v10, v0
	v_mov_b32_e32 v11, v0
	v_mov_b32_e32 v12, v0
	v_mov_b32_e32 v13, v0
	v_mov_b64_e32 v[32:33], v[14:15]
	v_mov_b64_e32 v[30:31], v[12:13]
	v_mov_b64_e32 v[28:29], v[10:11]
	v_mov_b64_e32 v[26:27], v[8:9]
	v_mov_b64_e32 v[24:25], v[6:7]
	v_mov_b64_e32 v[22:23], v[4:5]
	v_mov_b64_e32 v[20:21], v[2:3]
	v_mov_b64_e32 v[18:19], v[0:1]
	v_mov_b64_e32 v[16:17], v[14:15]
	s_mov_b32 s10, 0x800000
	s_mov_b32 s23, 0
	s_mov_b32 s51, s35
	v_or_b32_e32 v121, 31, v123
	v_lshl_add_u64 v[128:129], s[6:7], 0, v[110:111]
	v_lshl_add_u64 v[130:131], s[4:5], 0, v[108:109]
	v_lshl_add_u64 v[132:133], s[6:7], 0, v[114:115]
	v_lshl_add_u64 v[134:135], s[4:5], 0, v[112:113]
	v_lshl_add_u64 v[136:137], s[6:7], 0, v[118:119]
	v_lshl_add_u64 v[138:139], s[4:5], 0, v[116:117]
	v_readfirstlane_b32 s100, v140
	v_add_u32_e32 v188, v142, v144
	v_add_u32_e32 v189, v142, v145
	v_add_u32_e32 v190, v142, v146
	v_add_u32_e32 v191, v142, v147
	v_add_u32_e32 v192, v142, v152
	v_add_u32_e32 v193, v142, v153
	v_add_u32_e32 v194, v143, v154
	v_add_u32_e32 v195, v143, v155
	v_add_u32_e32 v196, v143, v156
	v_add_u32_e32 v197, v143, v157
	v_add_u32_e32 v198, v143, v158
	v_add_u32_e32 v199, v143, v159
	v_add_u32_e32 v200, v143, v160
	v_add_u32_e32 v201, v143, v161
	v_mov_b32_e32 v34, v180
	v_ashrrev_i32_e32 v35, 31, v34
	v_lshlrev_b64 v[36:37], 10, v[34:35]
	v_lshlrev_b64 v[34:35], 6, v[34:35]
	v_lshl_add_u64 v[34:35], v[128:129], 0, v[34:35]
	v_lshl_add_u64 v[36:37], v[130:131], 0, v[36:37]
	v_lshl_add_u64 v[34:35], v[34:35], 0, s[36:37]
	v_cndmask_b32_e64 v209, v35, v37, s[38:39]
	v_cndmask_b32_e64 v208, v34, v36, s[38:39]
	v_mov_b32_e32 v214, 0x1000
	v_mov_b32_e32 v34, 0x10000
	v_cndmask_b32_e64 v214, v214, v34, s[38:39]
	v_mov_b32_e32 v215, 0
	v_mov_b32_e32 v34, v179
	v_ashrrev_i32_e32 v35, 31, v34
	v_lshlrev_b64 v[36:37], 10, v[34:35]
	v_lshlrev_b64 v[34:35], 6, v[34:35]
	v_lshl_add_u64 v[34:35], v[132:133], 0, v[34:35]
	v_lshl_add_u64 v[36:37], v[134:135], 0, v[36:37]
	v_lshl_add_u64 v[34:35], v[34:35], 0, s[36:37]
	v_cndmask_b32_e64 v211, v35, v37, s[40:41]
	v_cndmask_b32_e64 v210, v34, v36, s[40:41]
	v_mov_b32_e32 v216, 0x1000
	v_mov_b32_e32 v34, 0x10000
	v_cndmask_b32_e64 v216, v216, v34, s[40:41]
	v_mov_b32_e32 v217, 0
	v_mov_b32_e32 v34, v178
	v_ashrrev_i32_e32 v35, 31, v34
	v_lshlrev_b64 v[36:37], 10, v[34:35]
	v_lshlrev_b64 v[34:35], 6, v[34:35]
	v_lshl_add_u64 v[34:35], v[136:137], 0, v[34:35]
	v_lshl_add_u64 v[36:37], v[138:139], 0, v[36:37]
	v_lshl_add_u64 v[34:35], v[34:35], 0, s[36:37]
	v_cndmask_b32_e64 v213, v35, v37, s[42:43]
	v_cndmask_b32_e64 v212, v34, v36, s[42:43]
	v_mov_b32_e32 v218, 0x1000
	v_mov_b32_e32 v34, 0x10000
	v_cndmask_b32_e64 v218, v218, v34, s[42:43]
	v_mov_b32_e32 v219, 0
	v_mov_b32_e32 v182, 0xff800000
	v_mov_b32_e32 v181, 0
	v_mov_b64_e32 v[14:15], v[12:13]
	v_mov_b64_e32 v[12:13], v[10:11]
	v_mov_b64_e32 v[10:11], v[8:9]
	v_mov_b64_e32 v[8:9], v[6:7]
	v_mov_b64_e32 v[6:7], v[4:5]
	v_mov_b64_e32 v[4:5], v[2:3]
	v_mov_b64_e32 v[2:3], v[0:1]
	s_mov_b32 s4, 0
	s_waitcnt vmcnt(0)

; #define LAS __attribute__((address_space(3)))
; DI int crow(int r, int hh) { return (r & 3) + 8 * (r >> 2) + 4 * hh; }
; DI void phase_attn(const Params& p, int l, LAS char* lds) {
;     ...
;             LAS char* st = lds + (kt & 1) * 20480;
;             f32x16 s0, s1;
; #pragma unroll
;             for (int r = 0; r < 16; ++r) { s0[r] = 0.f; s1[r] = 0.f; }
; #pragma unroll
;             for (int s = 0; s < 6; ++s) {
;                 const int pos = ((2 * s + hh) ^ ksw) << 4;
;                 const bf16x8 k0 = *(LAS bf16x8*)(st + qi * 192 + pos);
;                 const bf16x8 k1 = *(LAS bf16x8*)(st + (qi + 32) * 192 + pos);
;                 s0 = __builtin_amdgcn_mfma_f32_32x32x16_bf16(k0, qf[s], s0, 0, 0, 0);
;                 s1 = __builtin_amdgcn_mfma_f32_32x32x16_bf16(k1, qf[s], s1, 0, 0, 0);
;             }
;             if (kt * 64 + 63 > q0w) {
;                 const int qpos = q0w + qi;
; #pragma unroll
;                 for (int r = 0; r < 16; ++r) {
;                     const int key = kt * 64 + crow(r, hh);
;                     if (key > qpos) s0[r] = -INFINITY;
;                     if (key + 32 > qpos) s1[r] = -INFINITY;
;                 }
;             }
.LBB0_288:
	s_bitcmp1_b32 s4, 0
	s_cselect_b32 s34, 0x5000, 0
	s_cbranch_scc1 .Lqk_s1
	ds_read_b128 v[34:37], v188 offset:0
	ds_read_b128 v[184:187], v189 offset:0
	ds_read_b128 v[50:53], v188 offset:6144
	s_add_i32 s4, s23, 63
	v_cmp_gt_i32_e32 vcc, s4, v123
	s_waitcnt lgkmcnt(0)
	v_mfma_f32_32x32x16_bf16 v[34:49], v[34:37], v[66:69], 0
	v_mfma_f32_32x32x16_bf16 v[34:49], v[184:187], v[70:73], v[34:49]
	ds_read_b128 v[184:187], v189 offset:6144
	v_mfma_f32_32x32x16_bf16 v[50:65], v[50:53], v[66:69], 0
	s_waitcnt lgkmcnt(0)
	v_mfma_f32_32x32x16_bf16 v[50:65], v[184:187], v[70:73], v[50:65]
	ds_read_b128 v[184:187], v190 offset:0
	s_waitcnt lgkmcnt(0)
	v_mfma_f32_32x32x16_bf16 v[34:49], v[184:187], v[74:77], v[34:49]
	ds_read_b128 v[184:187], v190 offset:6144
	s_waitcnt lgkmcnt(0)
	v_mfma_f32_32x32x16_bf16 v[50:65], v[184:187], v[74:77], v[50:65]
	ds_read_b128 v[184:187], v191 offset:0
	s_waitcnt lgkmcnt(0)
	v_mfma_f32_32x32x16_bf16 v[34:49], v[184:187], v[78:81], v[34:49]
	ds_read_b128 v[184:187], v191 offset:6144
	s_waitcnt lgkmcnt(0)
	v_mfma_f32_32x32x16_bf16 v[50:65], v[184:187], v[78:81], v[50:65]
	ds_read_b128 v[184:187], v192 offset:0
	s_waitcnt lgkmcnt(0)
	v_mfma_f32_32x32x16_bf16 v[34:49], v[184:187], v[82:85], v[34:49]
	ds_read_b128 v[184:187], v192 offset:6144
	s_waitcnt lgkmcnt(0)
	v_mfma_f32_32x32x16_bf16 v[50:65], v[184:187], v[82:85], v[50:65]
	ds_read_b128 v[184:187], v193 offset:0
	s_waitcnt lgkmcnt(0)
	v_mfma_f32_32x32x16_bf16 v[34:49], v[184:187], v[86:89], v[34:49]
	ds_read_b128 v[184:187], v193 offset:6144
	s_waitcnt lgkmcnt(0)
	v_mfma_f32_32x32x16_bf16 v[50:65], v[184:187], v[86:89], v[50:65]
	s_branch .Lqk_done
.Lqk_s1:
	ds_read_b128 v[34:37], v188 offset:20480
	ds_read_b128 v[184:187], v189 offset:20480
	ds_read_b128 v[50:53], v188 offset:26624
	s_add_i32 s4, s23, 63
	v_cmp_gt_i32_e32 vcc, s4, v123
	s_waitcnt lgkmcnt(0)
	v_mfma_f32_32x32x16_bf16 v[34:49], v[34:37], v[66:69], 0
	v_mfma_f32_32x32x16_bf16 v[34:49], v[184:187], v[70:73], v[34:49]
	ds_read_b128 v[184:187], v189 offset:26624
	v_mfma_f32_32x32x16_bf16 v[50:65], v[50:53], v[66:69], 0
	s_waitcnt lgkmcnt(0)
	v_mfma_f32_32x32x16_bf16 v[50:65], v[184:187], v[70:73], v[50:65]
	ds_read_b128 v[184:187], v190 offset:20480
	s_waitcnt lgkmcnt(0)
	v_mfma_f32_32x32x16_bf16 v[34:49], v[184:187], v[74:77], v[34:49]
	ds_read_b128 v[184:187], v190 offset:26624
	s_waitcnt lgkmcnt(0)
	v_mfma_f32_32x32x16_bf16 v[50:65], v[184:187], v[74:77], v[50:65]
	ds_read_b128 v[184:187], v191 offset:20480
	s_waitcnt lgkmcnt(0)
	v_mfma_f32_32x32x16_bf16 v[34:49], v[184:187], v[78:81], v[34:49]
	ds_read_b128 v[184:187], v191 offset:26624
	s_waitcnt lgkmcnt(0)
	v_mfma_f32_32x32x16_bf16 v[50:65], v[184:187], v[78:81], v[50:65]
	ds_read_b128 v[184:187], v192 offset:20480
	s_waitcnt lgkmcnt(0)
	v_mfma_f32_32x32x16_bf16 v[34:49], v[184:187], v[82:85], v[34:49]
	ds_read_b128 v[184:187], v192 offset:26624
	s_waitcnt lgkmcnt(0)
	v_mfma_f32_32x32x16_bf16 v[50:65], v[184:187], v[82:85], v[50:65]
	ds_read_b128 v[184:187], v193 offset:20480
	s_waitcnt lgkmcnt(0)
	v_mfma_f32_32x32x16_bf16 v[34:49], v[184:187], v[86:89], v[34:49]
	ds_read_b128 v[184:187], v193 offset:26624
	s_waitcnt lgkmcnt(0)
	v_mfma_f32_32x32x16_bf16 v[50:65], v[184:187], v[86:89], v[50:65]
.Lqk_done:
	s_and_saveexec_b64 s[52:53], vcc
	s_cbranch_execz .LBB0_290
	v_add_u32_e32 v1, s23, v90
	v_add_u32_e32 v183, 32, v1
	v_cmp_le_i32_e32 vcc, v183, v122
	v_add_u32_e32 v183, 33, v1
	s_nop 5
	v_cndmask_b32_e32 v50, v170, v50, vcc
	v_cmp_lt_i32_e32 vcc, v1, v122
	s_nop 1
	v_cndmask_b32_e32 v35, v170, v35, vcc
	v_cmp_le_i32_e32 vcc, v1, v122
	s_nop 1
	v_cndmask_b32_e32 v34, v170, v34, vcc
	v_cmp_le_i32_e32 vcc, v183, v122
	v_add_u32_e32 v183, 2, v1
	s_nop 0
	v_cndmask_b32_e32 v51, v170, v51, vcc
	v_cmp_le_i32_e32 vcc, v183, v122
	v_add_u32_e32 v183, 34, v1
	s_nop 0
	v_cndmask_b32_e32 v36, v170, v36, vcc
	v_cmp_le_i32_e32 vcc, v183, v122
	v_add_u32_e32 v183, 3, v1
	s_nop 0
	v_cndmask_b32_e32 v52, v170, v52, vcc
	v_cmp_le_i32_e32 vcc, v183, v122
	v_add_u32_e32 v183, 35, v1
	s_nop 0
	v_cndmask_b32_e32 v37, v170, v37, vcc
	v_cmp_le_i32_e32 vcc, v183, v122
	v_add_u32_e32 v183, 8, v1
	s_nop 0
	v_cndmask_b32_e32 v53, v170, v53, vcc
	v_cmp_le_i32_e32 vcc, v183, v122
	v_add_u32_e32 v183, 40, v1
	s_nop 0
	v_cndmask_b32_e32 v38, v170, v38, vcc
	v_cmp_le_i32_e32 vcc, v183, v122
	v_add_u32_e32 v183, 9, v1
	s_nop 0
	v_cndmask_b32_e32 v54, v170, v54, vcc
	v_cmp_le_i32_e32 vcc, v183, v122
	v_add_u32_e32 v183, 41, v1
	s_nop 0
	v_cndmask_b32_e32 v39, v170, v39, vcc
	v_cmp_le_i32_e32 vcc, v183, v122
	v_add_u32_e32 v183, 10, v1
	s_nop 0
	v_cndmask_b32_e32 v55, v170, v55, vcc
	v_cmp_le_i32_e32 vcc, v183, v122
	v_add_u32_e32 v183, 42, v1
	s_nop 0
	v_cndmask_b32_e32 v40, v170, v40, vcc
	v_cmp_le_i32_e32 vcc, v183, v122
	v_add_u32_e32 v183, 11, v1
	s_nop 0
	v_cndmask_b32_e32 v56, v170, v56, vcc
	v_cmp_le_i32_e32 vcc, v183, v122
	v_add_u32_e32 v183, 43, v1
	s_nop 0
	v_cndmask_b32_e32 v41, v170, v41, vcc
	v_cmp_le_i32_e32 vcc, v183, v122
	v_add_u32_e32 v183, 16, v1
	s_nop 0
	v_cndmask_b32_e32 v57, v170, v57, vcc
	v_cmp_le_i32_e32 vcc, v183, v122
	v_add_u32_e32 v183, 48, v1
	s_nop 0
	v_cndmask_b32_e32 v42, v170, v42, vcc
	v_cmp_le_i32_e32 vcc, v183, v122
	v_add_u32_e32 v183, 17, v1
	s_nop 0
	v_cndmask_b32_e32 v58, v170, v58, vcc
	v_cmp_le_i32_e32 vcc, v183, v122
	v_add_u32_e32 v183, 49, v1
	s_nop 0
	v_cndmask_b32_e32 v43, v170, v43, vcc
	v_cmp_le_i32_e32 vcc, v183, v122
	v_add_u32_e32 v183, 18, v1
	s_nop 0
	v_cndmask_b32_e32 v59, v170, v59, vcc
	v_cmp_le_i32_e32 vcc, v183, v122
	v_add_u32_e32 v183, 50, v1
	s_nop 0
	v_cndmask_b32_e32 v44, v170, v44, vcc
	v_cmp_le_i32_e32 vcc, v183, v122
	v_add_u32_e32 v183, 19, v1
	s_nop 0
	v_cndmask_b32_e32 v60, v170, v60, vcc
	v_cmp_le_i32_e32 vcc, v183, v122
	v_add_u32_e32 v183, 51, v1
	s_nop 0
	v_cndmask_b32_e32 v45, v170, v45, vcc
	v_cmp_le_i32_e32 vcc, v183, v122
	v_add_u32_e32 v183, 24, v1
	s_nop 0
	v_cndmask_b32_e32 v61, v170, v61, vcc
	v_cmp_le_i32_e32 vcc, v183, v122
	v_add_u32_e32 v183, 56, v1
	s_nop 0
	v_cndmask_b32_e32 v46, v170, v46, vcc
	v_cmp_le_i32_e32 vcc, v183, v122
	v_add_u32_e32 v183, 25, v1
	s_nop 0
	v_cndmask_b32_e32 v62, v170, v62, vcc
	v_cmp_le_i32_e32 vcc, v183, v122
	v_add_u32_e32 v183, 57, v1
	s_nop 0
	v_cndmask_b32_e32 v47, v170, v47, vcc
	v_cmp_le_i32_e32 vcc, v183, v122
	v_add_u32_e32 v183, 26, v1
	s_nop 0
	v_cndmask_b32_e32 v63, v170, v63, vcc
	v_cmp_le_i32_e32 vcc, v183, v122
	v_add_u32_e32 v183, 58, v1
	s_nop 0
	v_cndmask_b32_e32 v48, v170, v48, vcc
	v_cmp_le_i32_e32 vcc, v183, v122
	v_add_u32_e32 v183, 27, v1
	v_add_u32_e32 v1, 59, v1
	v_cndmask_b32_e32 v64, v170, v64, vcc
	v_cmp_le_i32_e32 vcc, v183, v122
	s_nop 1
	v_cndmask_b32_e32 v49, v170, v49, vcc
	v_cmp_le_i32_e32 vcc, v1, v122
	s_nop 1
	v_cndmask_b32_e32 v65, v170, v65, vcc

; #define LAS __attribute__((address_space(3)))
; DI unsigned pk2(float lo, float hi) { f32x2 v = {lo, hi}; bf2_t r = __builtin_convertvector(v, bf2_t); return __builtin_bit_cast(unsigned, r); }
; DI void phase_attn(const Params& p, int l, LAS char* lds) {
;     ...
;             float ps = 0.f;
; #pragma unroll
;             for (int r = 0; r < 16; ++r) { s0[r] = __builtin_amdgcn_exp2f(s0[r] - m_new); s1[r] = __builtin_amdgcn_exp2f(s1[r] - m_new); ps += s0[r] + s1[r]; }
;             l_run += ps;
;             bf16x8 pf[2][2];
; #pragma unroll
;             for (int s2 = 0; s2 < 2; ++s2) {
;                 u32x4 a, c2;
; #pragma unroll
;                 for (int e = 0; e < 4; ++e) { a[e] = pk2(s0[8 * s2 + 2 * e], s0[8 * s2 + 2 * e + 1]); c2[e] = pk2(s1[8 * s2 + 2 * e], s1[8 * s2 + 2 * e + 1]); }
;                 pf[0][s2] = __builtin_bit_cast(bf16x8, a); pf[1][s2] = __builtin_bit_cast(bf16x8, c2);
;             }
;             LAS char* vs = st + 12288;
;             __builtin_amdgcn_s_setprio(0);
; #pragma unroll
;             for (int tl = 0; tl < 2; ++tl)
; #pragma unroll
;                 for (int s2 = 0; s2 < 2; ++s2) {
;                     const int c = 4 * tl + 2 * s2;
;                     const int p0 = ((c ^ vsw) << 4) + 8 * hh, p1 = (((c + 1) ^ vsw) << 4) + 8 * hh;
;                     const s16x4 a0 = *(LAS s16x4*)(vs + qi * 128 + p0), a1 = *(LAS s16x4*)(vs + qi * 128 + p1);
;                     const s16x4 b0 = *(LAS s16x4*)(vs + (qi + 32) * 128 + p0), b1 = *(LAS s16x4*)(vs + (qi + 32) * 128 + p1);
;                     const bf16x8 v0 = __builtin_shufflevector(a0, a1, 0, 1, 2, 3, 4, 5, 6, 7);
;                     const bf16x8 v1 = __builtin_shufflevector(b0, b1, 0, 1, 2, 3, 4, 5, 6, 7);
;                     o0 = __builtin_amdgcn_mfma_f32_32x32x16_bf16(v0, pf[tl][s2], o0, 0, 0, 0);
;                     o1 = __builtin_amdgcn_mfma_f32_32x32x16_bf16(v1, pf[tl][s2], o1, 0, 0, 0);
;                 }
.LBB0_292:
	v_sub_f32_e32 v34, v34, v182
	v_sub_f32_e32 v35, v35, v182
	v_sub_f32_e32 v36, v36, v182
	v_sub_f32_e32 v37, v37, v182
	v_sub_f32_e32 v38, v38, v182
	v_sub_f32_e32 v39, v39, v182
	v_sub_f32_e32 v40, v40, v182
	v_sub_f32_e32 v41, v41, v182
	v_sub_f32_e32 v42, v42, v182
	v_sub_f32_e32 v43, v43, v182
	v_sub_f32_e32 v44, v44, v182
	v_sub_f32_e32 v45, v45, v182
	v_sub_f32_e32 v46, v46, v182
	v_sub_f32_e32 v47, v47, v182
	v_sub_f32_e32 v48, v48, v182
	v_sub_f32_e32 v49, v49, v182
	v_sub_f32_e32 v50, v50, v182
	v_sub_f32_e32 v51, v51, v182
	v_sub_f32_e32 v52, v52, v182
	v_sub_f32_e32 v53, v53, v182
	v_sub_f32_e32 v54, v54, v182
	v_sub_f32_e32 v55, v55, v182
	v_sub_f32_e32 v56, v56, v182
	v_sub_f32_e32 v57, v57, v182
	v_sub_f32_e32 v58, v58, v182
	v_sub_f32_e32 v59, v59, v182
	v_sub_f32_e32 v60, v60, v182
	v_sub_f32_e32 v61, v61, v182
	v_sub_f32_e32 v62, v62, v182
	v_sub_f32_e32 v63, v63, v182
	v_sub_f32_e32 v64, v64, v182
	v_sub_f32_e32 v65, v65, v182
	v_exp_f32_e32 v34, v34
	v_exp_f32_e32 v35, v35
	v_exp_f32_e32 v36, v36
	v_exp_f32_e32 v37, v37
	v_exp_f32_e32 v38, v38
	v_exp_f32_e32 v39, v39
	v_exp_f32_e32 v40, v40
	v_exp_f32_e32 v41, v41
	v_exp_f32_e32 v42, v42
	v_exp_f32_e32 v43, v43
	v_exp_f32_e32 v44, v44
	v_exp_f32_e32 v45, v45
	v_exp_f32_e32 v46, v46
	v_exp_f32_e32 v47, v47
	v_exp_f32_e32 v48, v48
	v_exp_f32_e32 v49, v49
	v_exp_f32_e32 v50, v50
	v_exp_f32_e32 v51, v51
	v_exp_f32_e32 v52, v52
	v_exp_f32_e32 v53, v53
	v_exp_f32_e32 v54, v54
	v_exp_f32_e32 v55, v55
	v_exp_f32_e32 v56, v56
	v_exp_f32_e32 v57, v57
	v_exp_f32_e32 v58, v58
	v_exp_f32_e32 v59, v59
	v_exp_f32_e32 v60, v60
	v_exp_f32_e32 v61, v61
	v_exp_f32_e32 v62, v62
	v_exp_f32_e32 v63, v63
	v_exp_f32_e32 v64, v64
	v_exp_f32_e32 v65, v65
	v_add_f32_e32 v184, v34, v35
	v_add_f32_e32 v185, v50, v51
	v_add_f32_e32 v186, v36, v37
	v_add_f32_e32 v187, v52, v53
	v_add_f32_e32 v184, v184, v38
	v_add_f32_e32 v185, v185, v54
	v_add_f32_e32 v186, v186, v39
	v_add_f32_e32 v187, v187, v55
	v_add_f32_e32 v184, v184, v40
	v_add_f32_e32 v185, v185, v56
	v_add_f32_e32 v186, v186, v41
	v_add_f32_e32 v187, v187, v57
	v_add_f32_e32 v184, v184, v42
	v_add_f32_e32 v185, v185, v58
	v_add_f32_e32 v186, v186, v43
	v_add_f32_e32 v187, v187, v59
	v_add_f32_e32 v184, v184, v44
	v_add_f32_e32 v185, v185, v60
	v_add_f32_e32 v186, v186, v45
	v_add_f32_e32 v187, v187, v61
	v_add_f32_e32 v184, v184, v46
	v_add_f32_e32 v185, v185, v62
	v_add_f32_e32 v186, v186, v47
	v_add_f32_e32 v187, v187, v63
	v_add_f32_e32 v184, v184, v48
	v_add_f32_e32 v185, v185, v64
	v_add_f32_e32 v186, v186, v49
	v_add_f32_e32 v187, v187, v65
	v_add_f32_e32 v184, v184, v186
	v_add_f32_e32 v185, v185, v187
	v_add_f32_e32 v1, v184, v185
	v_cvt_pk_bf16_f32 v34, v34, v35
	v_cvt_pk_bf16_f32 v35, v36, v37
	v_cvt_pk_bf16_f32 v36, v38, v39
	v_cvt_pk_bf16_f32 v37, v40, v41
	v_cvt_pk_bf16_f32 v38, v42, v43
	v_cvt_pk_bf16_f32 v39, v44, v45
	v_cvt_pk_bf16_f32 v40, v46, v47
	v_cvt_pk_bf16_f32 v41, v48, v49
	v_cvt_pk_bf16_f32 v42, v50, v51
	v_cvt_pk_bf16_f32 v43, v52, v53
	v_cvt_pk_bf16_f32 v44, v54, v55
	v_cvt_pk_bf16_f32 v45, v56, v57
	v_cvt_pk_bf16_f32 v46, v58, v59
	v_cvt_pk_bf16_f32 v47, v60, v61
	v_cvt_pk_bf16_f32 v48, v62, v63
	v_cvt_pk_bf16_f32 v49, v64, v65
	v_add_f32_e32 v181, v181, v1
	s_setprio 0
	s_cmp_eq_u32 s34, 0
	s_cbranch_scc0 .Lpv_s1
	ds_read_b64 v[50:51], v194 offset:12288
	ds_read_b64 v[54:55], v194 offset:16384
	ds_read_b64 v[52:53], v195 offset:12288
	ds_read_b64 v[56:57], v195 offset:16384
	ds_read_b64 v[58:59], v196 offset:12288
	ds_read_b64 v[62:63], v196 offset:16384
	ds_read_b64 v[60:61], v197 offset:12288
	ds_read_b64 v[64:65], v197 offset:16384
	ds_read_b64 a[0:1], v198 offset:12288
	ds_read_b64 a[4:5], v198 offset:16384
	ds_read_b64 a[2:3], v199 offset:12288
	ds_read_b64 a[6:7], v199 offset:16384
	ds_read_b64 a[8:9], v200 offset:12288
	ds_read_b64 a[12:13], v200 offset:16384
	ds_read_b64 a[10:11], v201 offset:12288
	ds_read_b64 a[14:15], v201 offset:16384
	s_branch .Lpv_rd
.Lpv_s1:
	ds_read_b64 v[50:51], v194 offset:32768
	ds_read_b64 v[54:55], v194 offset:36864
	ds_read_b64 v[52:53], v195 offset:32768
	ds_read_b64 v[56:57], v195 offset:36864
	ds_read_b64 v[58:59], v196 offset:32768
	ds_read_b64 v[62:63], v196 offset:36864
	ds_read_b64 v[60:61], v197 offset:32768
	ds_read_b64 v[64:65], v197 offset:36864
	ds_read_b64 a[0:1], v198 offset:32768
	ds_read_b64 a[4:5], v198 offset:36864
	ds_read_b64 a[2:3], v199 offset:32768
	ds_read_b64 a[6:7], v199 offset:36864
	ds_read_b64 a[8:9], v200 offset:32768
	ds_read_b64 a[12:13], v200 offset:36864
	ds_read_b64 a[10:11], v201 offset:32768
	ds_read_b64 a[14:15], v201 offset:36864
.Lpv_rd:
	s_waitcnt lgkmcnt(12)
	v_mfma_f32_32x32x16_bf16 v[18:33], v[50:53], v[34:37], v[18:33]
	v_mfma_f32_32x32x16_bf16 v[2:17], v[54:57], v[34:37], v[2:17]
	s_waitcnt lgkmcnt(8)
	v_mfma_f32_32x32x16_bf16 v[18:33], v[58:61], v[38:41], v[18:33]
	v_mfma_f32_32x32x16_bf16 v[2:17], v[62:65], v[38:41], v[2:17]
	s_waitcnt lgkmcnt(4)
	v_mfma_f32_32x32x16_bf16 v[18:33], a[0:3], v[42:45], v[18:33]
	v_mfma_f32_32x32x16_bf16 v[2:17], a[4:7], v[42:45], v[2:17]
	s_waitcnt lgkmcnt(0)
	v_mfma_f32_32x32x16_bf16 v[18:33], a[8:11], v[46:49], v[18:33]
	v_mfma_f32_32x32x16_bf16 v[2:17], a[12:15], v[46:49], v[2:17]
	s_or_b64 exec, exec, s[48:49]
	s_add_i32 s23, s23, 64
	s_cmp_eq_u32 s1, s33
	s_cbranch_scc1 .LBB0_294
